# P4 tile order in panels of 8 row tiles (8 A + 4 B tiles shared per XCD)
# baseline (speedup 1.0000x reference)
.LBB0_1087:
	s_mul_hi_i32 s2, s49, 0x2e8ba2e9
	s_lshr_b32 s3, s2, 31
	s_ashr_i32 s2, s2, 5
	s_add_i32 s2, s2, s3
	s_lshl_b32 s3, s2, 3
	s_sub_i32 s4, s7, s3
	s_min_i32 s4, s4, 8
	s_abs_i32 s5, s4
	v_cvt_f32_u32_e32 v3, s5
	s_sub_i32 s20, 0, s5
	s_mulk_i32 s2, 0xff50
	s_add_i32 s2, s2, s49
	v_rcp_iflag_f32_e32 v3, v3
	s_abs_i32 s19, s2
	s_xor_b32 s18, s2, s4
	s_ashr_i32 s18, s18, 31
	v_mul_f32_e32 v3, 0x4f7ffffe, v3
	v_cvt_u32_f32_e32 v3, v3
	v_mov_b32_e32 v1, v222
	v_mov_b32_e32 v9, v211
	v_readfirstlane_b32 s21, v3
	s_mul_i32 s20, s20, s21
	s_mul_hi_u32 s20, s21, s20
	s_add_i32 s21, s21, s20
	s_mul_hi_u32 s20, s19, s21
	s_mul_i32 s21, s20, s5
	s_sub_i32 s19, s19, s21
	s_add_i32 s21, s20, 1
	s_sub_i32 s22, s19, s5
	s_cmp_ge_u32 s19, s5
	s_cselect_b32 s20, s21, s20
	s_cselect_b32 s19, s22, s19
	s_add_i32 s21, s20, 1
	s_cmp_ge_u32 s19, s5
	s_cselect_b32 s5, s21, s20
	s_xor_b32 s5, s5, s18
	s_sub_i32 s18, s5, s18
	s_mul_i32 s4, s18, s4
	s_sub_i32 s2, s2, s4
	s_add_i32 s2, s2, s3
	s_mul_i32 s28, s2, 0xfe
	s_add_i32 s28, s28, -1
	v_lshrrev_b32_e32 v202, 3, v222
	v_lshrrev_b32_e32 v203, 4, v222
	v_xor_b32_e32 v203, v203, v222
	v_and_b32_e32 v203, 7, v203
	v_lshlrev_b32_e32 v210, 4, v203
	v_mov_b32_e32 v200, s46
	v_mov_b32_e32 v201, s47
	v_add_u32_e32 v204, s28, v202
	v_mov_b32_e32 v205, 0
	v_cmp_gt_u32_e32 vcc, s6, v204
	v_lshlrev_b64 v[196:197], 11, v[204:205]
	v_lshl_add_u64 v[196:197], s[64:65], 0, v[196:197]
	v_cndmask_b32_e32 v196, v200, v196, vcc
	v_cndmask_b32_e32 v197, v201, v197, vcc
	v_lshl_add_u64 v[218:219], v[196:197], 0, v[210:211]
	v_add_u32_e32 v204, 64, v204
	v_cmp_gt_u32_e32 vcc, s6, v204
	v_lshlrev_b64 v[196:197], 11, v[204:205]
	v_lshl_add_u64 v[196:197], s[64:65], 0, v[196:197]
	v_cndmask_b32_e32 v196, v200, v196, vcc
	v_cndmask_b32_e32 v197, v201, v197, vcc
	v_lshl_add_u64 v[220:221], v[196:197], 0, v[210:211]
	v_add_u32_e32 v204, 64, v204
	v_cmp_gt_u32_e32 vcc, s6, v204
	v_lshlrev_b64 v[196:197], 11, v[204:205]
	v_lshl_add_u64 v[196:197], s[64:65], 0, v[196:197]
	v_cndmask_b32_e32 v196, v200, v196, vcc
	v_cndmask_b32_e32 v197, v201, v197, vcc
	v_lshl_add_u64 v[224:225], v[196:197], 0, v[210:211]
	v_add_u32_e32 v204, 64, v204
	v_cmp_gt_u32_e32 vcc, s6, v204
	v_lshlrev_b64 v[196:197], 11, v[204:205]
	v_lshl_add_u64 v[196:197], s[64:65], 0, v[196:197]
	v_cndmask_b32_e32 v196, v200, v196, vcc
	v_cndmask_b32_e32 v197, v201, v197, vcc
	v_lshl_add_u64 v[226:227], v[196:197], 0, v[210:211]
	s_lshl_b32 s2, s18, 19
	s_add_u32 s2, s55, s2
	s_addc_u32 s3, s48, 0
	v_lshlrev_b32_e32 v196, 11, v202
	v_add_u32_e32 v196, v196, v210
	v_mov_b32_e32 v197, 0
	v_lshl_add_u64 v[228:229], v[196:197], 0, s[2:3]
	v_readfirstlane_b32 s19, v222
	s_nop 3
	s_lshr_b32 s29, s19, 8
	s_lshr_b32 s19, s19, 6
	s_lshl_b32 s19, s19, 10
	s_barrier
	s_mov_b32 s20, 0
	s_mov_b32 s21, 0
	s_mov_b32 s23, 0
	s_mov_b32 m0, s19
	v_lshl_add_u64 v[196:197], v[218:219], 0, s[20:21]
	global_load_lds_dwordx4 v[196:197], off
	s_add_i32 m0, s19, 0x2000
	v_lshl_add_u64 v[198:199], v[220:221], 0, s[20:21]
	global_load_lds_dwordx4 v[198:199], off
	s_add_i32 m0, s19, 0x4000
	v_lshl_add_u64 v[196:197], v[224:225], 0, s[20:21]
	global_load_lds_dwordx4 v[196:197], off
	s_add_i32 m0, s19, 0x6000
	v_lshl_add_u64 v[198:199], v[226:227], 0, s[20:21]
	global_load_lds_dwordx4 v[198:199], off
	s_add_i32 m0, s19, 0x8000
	v_lshl_add_u64 v[196:197], v[228:229], 0, s[20:21]
	global_load_lds_dwordx4 v[196:197], off
	s_add_u32 s22, s20, 0x20000
	s_add_i32 m0, s19, 0xa000
	v_lshl_add_u64 v[198:199], v[228:229], 0, s[22:23]
	global_load_lds_dwordx4 v[198:199], off
	s_add_u32 s22, s20, 0x40000
	s_add_i32 m0, s19, 0xc000
	v_lshl_add_u64 v[196:197], v[228:229], 0, s[22:23]
	global_load_lds_dwordx4 v[196:197], off
	s_add_u32 s22, s20, 0x60000
	s_add_i32 m0, s19, 0xe000
	v_lshl_add_u64 v[198:199], v[228:229], 0, s[22:23]
	global_load_lds_dwordx4 v[198:199], off
	s_waitcnt vmcnt(0)

.Lp4_skew1:
	s_nop 7
	s_nop 1
	s_mov_b32 s94, s18
	s_mov_b32 s34, s28
	v_bfe_u32 v201, v222, 6, 2
	v_bfe_u32 v202, v222, 4, 2
	v_lshlrev_b32_e32 v203, 2, v202
	v_lshl_or_b32 v203, v201, 5, v203
	s_lshl_b32 s4, s94, 7
	v_or_b32_e32 v204, s4, v203
	v_lshlrev_b32_e32 v205, 2, v204
	global_load_dwordx4 v[130:133], v205, s[10:11]
	global_load_dwordx4 v[134:137], v205, s[12:13]
	global_load_dwordx4 v[138:141], v205, s[14:15]
	global_load_dwordx4 v[142:145], v205, s[10:11] offset:64
	global_load_dwordx4 v[146:149], v205, s[12:13] offset:64
	global_load_dwordx4 v[150:153], v205, s[14:15] offset:64
	s_add_i32 s2, s49, s95
	s_cmp_lt_i32 s2, s58
	s_cselect_b32 s35, 1, 0
	s_cselect_b32 s49, s2, s49
	s_mul_hi_i32 s2, s49, 0x2e8ba2e9
	s_lshr_b32 s3, s2, 31
	s_ashr_i32 s2, s2, 5
	s_add_i32 s2, s2, s3
	s_lshl_b32 s3, s2, 3
	s_sub_i32 s4, s7, s3
	s_min_i32 s4, s4, 8
	s_abs_i32 s5, s4
	v_cvt_f32_u32_e32 v199, s5
	s_sub_i32 s20, 0, s5
	s_mulk_i32 s2, 0xff50
	s_add_i32 s2, s2, s49
	v_rcp_iflag_f32_e32 v199, v199
	s_abs_i32 s19, s2
	s_xor_b32 s18, s2, s4
	s_ashr_i32 s18, s18, 31
	v_mul_f32_e32 v199, 0x4f7ffffe, v199
	v_cvt_u32_f32_e32 v199, v199
	s_nop 1
	v_readfirstlane_b32 s21, v199
	s_mul_i32 s20, s20, s21
	s_mul_hi_u32 s20, s21, s20
	s_add_i32 s21, s21, s20
	s_mul_hi_u32 s20, s19, s21
	s_mul_i32 s21, s20, s5
	s_sub_i32 s19, s19, s21
	s_add_i32 s21, s20, 1
	s_sub_i32 s22, s19, s5
	s_cmp_ge_u32 s19, s5
	s_cselect_b32 s20, s21, s20
	s_cselect_b32 s19, s22, s19
	s_add_i32 s21, s20, 1
	s_cmp_ge_u32 s19, s5
	s_cselect_b32 s5, s21, s20
	s_xor_b32 s5, s5, s18
	s_sub_i32 s18, s5, s18
	s_mul_i32 s4, s18, s4
	s_sub_i32 s2, s2, s4
	s_add_i32 s2, s2, s3
	s_mul_i32 s28, s2, 0xfe
	s_add_i32 s28, s28, -1
	v_lshrrev_b32_e32 v202, 3, v222
	v_lshrrev_b32_e32 v203, 4, v222
	v_xor_b32_e32 v203, v203, v222
	v_and_b32_e32 v203, 7, v203
	v_lshlrev_b32_e32 v210, 4, v203
	v_mov_b32_e32 v200, s46
	v_mov_b32_e32 v201, s47
	v_add_u32_e32 v204, s28, v202
	v_mov_b32_e32 v205, 0
	v_cmp_gt_u32_e32 vcc, s6, v204
	v_lshlrev_b64 v[196:197], 11, v[204:205]
	v_lshl_add_u64 v[196:197], s[64:65], 0, v[196:197]
	v_cndmask_b32_e32 v196, v200, v196, vcc
	v_cndmask_b32_e32 v197, v201, v197, vcc
	v_lshl_add_u64 v[218:219], v[196:197], 0, v[210:211]
	v_add_u32_e32 v204, 64, v204
	v_cmp_gt_u32_e32 vcc, s6, v204
	v_lshlrev_b64 v[196:197], 11, v[204:205]
	v_lshl_add_u64 v[196:197], s[64:65], 0, v[196:197]
	v_cndmask_b32_e32 v196, v200, v196, vcc
	v_cndmask_b32_e32 v197, v201, v197, vcc
	v_lshl_add_u64 v[220:221], v[196:197], 0, v[210:211]
	v_add_u32_e32 v204, 64, v204
	v_cmp_gt_u32_e32 vcc, s6, v204
	v_lshlrev_b64 v[196:197], 11, v[204:205]
	v_lshl_add_u64 v[196:197], s[64:65], 0, v[196:197]
	v_cndmask_b32_e32 v196, v200, v196, vcc
	v_cndmask_b32_e32 v197, v201, v197, vcc
	v_lshl_add_u64 v[224:225], v[196:197], 0, v[210:211]
	v_add_u32_e32 v204, 64, v204
	v_cmp_gt_u32_e32 vcc, s6, v204
	v_lshlrev_b64 v[196:197], 11, v[204:205]
	v_lshl_add_u64 v[196:197], s[64:65], 0, v[196:197]
	v_cndmask_b32_e32 v196, v200, v196, vcc
	v_cndmask_b32_e32 v197, v201, v197, vcc
	v_lshl_add_u64 v[226:227], v[196:197], 0, v[210:211]
	s_lshl_b32 s2, s18, 19
	s_add_u32 s2, s55, s2
	s_addc_u32 s3, s48, 0
	v_lshlrev_b32_e32 v196, 11, v202
	v_add_u32_e32 v196, v196, v210
	v_mov_b32_e32 v197, 0
	v_lshl_add_u64 v[228:229], v[196:197], 0, s[2:3]
	v_readfirstlane_b32 s19, v222
	s_nop 3
	s_lshr_b32 s29, s19, 8
	s_lshr_b32 s19, s19, 6
	s_lshl_b32 s19, s19, 10
	s_mov_b32 s20, 0
	s_mov_b32 s21, 0
	s_mov_b32 s23, 0
	s_mov_b32 m0, s19
	v_lshl_add_u64 v[196:197], v[218:219], 0, s[20:21]
	global_load_lds_dwordx4 v[196:197], off
	s_add_i32 m0, s19, 0x2000
	v_lshl_add_u64 v[198:199], v[220:221], 0, s[20:21]
	global_load_lds_dwordx4 v[198:199], off
	s_add_i32 m0, s19, 0x4000
	v_lshl_add_u64 v[196:197], v[224:225], 0, s[20:21]
	global_load_lds_dwordx4 v[196:197], off
	s_add_i32 m0, s19, 0x6000
	v_lshl_add_u64 v[198:199], v[226:227], 0, s[20:21]
	global_load_lds_dwordx4 v[198:199], off
	s_add_i32 m0, s19, 0x8000
	v_lshl_add_u64 v[196:197], v[228:229], 0, s[20:21]
	global_load_lds_dwordx4 v[196:197], off
	s_add_u32 s22, s20, 0x20000
	s_add_i32 m0, s19, 0xa000
	v_lshl_add_u64 v[198:199], v[228:229], 0, s[22:23]
	global_load_lds_dwordx4 v[198:199], off
	s_add_u32 s22, s20, 0x40000
	s_add_i32 m0, s19, 0xc000
	v_lshl_add_u64 v[196:197], v[228:229], 0, s[22:23]
	global_load_lds_dwordx4 v[196:197], off
	s_add_u32 s22, s20, 0x60000
	s_add_i32 m0, s19, 0xe000
	v_lshl_add_u64 v[198:199], v[228:229], 0, s[22:23]
	global_load_lds_dwordx4 v[198:199], off
	v_and_b32_e32 v200, 15, v222
	v_lshrrev_b32_e32 v201, 8, v222
	v_lshl_or_b32 v200, v201, 7, v200
	v_bfe_u32 v201, v222, 6, 2
	v_bfe_u32 v202, v222, 4, 2
	v_lshlrev_b32_e32 v203, 2, v202
	v_lshl_or_b32 v203, v201, 5, v203
	s_lshl_b32 s4, s94, 7
	v_or_b32_e32 v204, s4, v203
	v_lshlrev_b32_e32 v205, 2, v204
	v_lshlrev_b32_e32 v207, 1, v204
	v_mul_u32_u24_e32 v206, 0x110, v200
	v_lshl_add_u32 v206, v203, 1, v206
	v_add_u32_e32 v206, 0x10000, v206
	v_cvt_pk_f16_f32 v170, v126, v127
	v_cvt_pk_f16_f32 v171, v128, v129
	v_cvt_pk_f16_f32 v172, v118, v119
	v_cvt_pk_f16_f32 v173, v120, v121
	ds_write2_b64 v206, v[170:171], v[172:173] offset1:4
	v_cvt_pk_f16_f32 v174, v110, v111
	v_cvt_pk_f16_f32 v175, v112, v113
	v_cvt_pk_f16_f32 v176, v102, v103
	v_cvt_pk_f16_f32 v177, v104, v105
	v_add_u32_e32 v178, 0x1100, v206
	ds_write2_b64 v178, v[174:175], v[176:177] offset1:4
	v_cvt_pk_f16_f32 v170, v94, v95
	v_cvt_pk_f16_f32 v171, v96, v97
	v_cvt_pk_f16_f32 v172, v86, v87
	v_cvt_pk_f16_f32 v173, v88, v89
	v_add_u32_e32 v178, 0x2200, v206
	ds_write2_b64 v178, v[170:171], v[172:173] offset1:4
	v_cvt_pk_f16_f32 v174, v78, v79
	v_cvt_pk_f16_f32 v175, v80, v81
	v_cvt_pk_f16_f32 v176, v70, v71
	v_cvt_pk_f16_f32 v177, v72, v73
	v_add_u32_e32 v178, 0x3300, v206
	ds_write2_b64 v178, v[174:175], v[176:177] offset1:4
	v_cvt_pk_f16_f32 v170, v62, v63
	v_cvt_pk_f16_f32 v171, v64, v65
	v_cvt_pk_f16_f32 v172, v54, v55
	v_cvt_pk_f16_f32 v173, v56, v57
	v_add_u32_e32 v178, 0x4400, v206
	ds_write2_b64 v178, v[170:171], v[172:173] offset1:4
	v_cvt_pk_f16_f32 v174, v46, v47
	v_cvt_pk_f16_f32 v175, v48, v49
	v_cvt_pk_f16_f32 v176, v38, v39
	v_cvt_pk_f16_f32 v177, v40, v41
	v_add_u32_e32 v178, 0x5500, v206
	ds_write2_b64 v178, v[174:175], v[176:177] offset1:4
	v_cvt_pk_f16_f32 v170, v30, v31
	v_cvt_pk_f16_f32 v171, v32, v33
	v_cvt_pk_f16_f32 v172, v22, v23
	v_cvt_pk_f16_f32 v173, v24, v25
	v_add_u32_e32 v178, 0x6600, v206
	ds_write2_b64 v178, v[170:171], v[172:173] offset1:4
	v_cvt_pk_f16_f32 v174, v14, v15
	v_cvt_pk_f16_f32 v175, v16, v17
	v_cvt_pk_f16_f32 v176, v6, v7
	v_cvt_pk_f16_f32 v177, v8, v9
	v_add_u32_e32 v178, 0x7700, v206
	ds_write2_b64 v178, v[174:175], v[176:177] offset1:4
	v_add_u32_e32 v201, 0xfffffef0, v206
	s_waitcnt lgkmcnt(0)
	s_barrier
	ds_read2_b64 v[154:157], v201 offset1:4
	ds_read2_b64 v[158:161], v201 offset0:68 offset1:72
	s_waitcnt vmcnt(8)
	v_add_u32_e32 v179, 0x1100, v201
	ds_read2_b64 v[162:165], v179 offset1:4
	ds_read2_b64 v[166:169], v179 offset0:68 offset1:72
	v_add_u32_e32 v180, 0, v200
	v_add_u32_e32 v181, s34, v180
	v_add_u32_e32 v182, -1, v180
	v_cmp_gt_u32_e32 vcc, 0xfe, v182
	v_cmp_gt_i32_e64 s[2:3], s6, v181
	v_cmp_gt_i32_e64 s[4:5], s68, v181
	v_mad_u32_u24 v183, v181, s52, v207
	s_and_b64 s[2:3], vcc, s[2:3]
	v_cndmask_b32_e64 v184, v216, v217, s[4:5]
	v_and_b32_e32 v185, v184, v181
	v_cmp_eq_u32_e32 vcc, 0, v185
	s_nop 1
	v_cndmask_b32_e64 v186, 1.0, 0, vcc
	v_cmp_eq_u32_e32 vcc, v185, v184
	s_nop 1
	v_cndmask_b32_e64 v188, 1.0, 0, vcc
	s_and_saveexec_b64 s[4:5], s[2:3]
	s_waitcnt lgkmcnt(2)
	v_pk_mul_f32 v[126:127], v[126:127], v[134:135]
	v_pk_mul_f32 v[128:129], v[128:129], v[136:137]
	v_pk_mul_f32 v[190:191], v[186:187], v[130:131] op_sel_hi:[0,1]
	v_pk_mul_f32 v[192:193], v[186:187], v[132:133] op_sel_hi:[0,1]
	v_cvt_f32_f16_e32 v194, v154
	v_cvt_f32_f16_sdwa v195, v154 dst_sel:DWORD dst_unused:UNUSED_PAD src0_sel:WORD_1
	v_cvt_f32_f16_e32 v196, v155
	v_cvt_f32_f16_sdwa v197, v155 dst_sel:DWORD dst_unused:UNUSED_PAD src0_sel:WORD_1
	v_pk_fma_f32 v[126:127], v[190:191], v[194:195], v[126:127]
	v_pk_fma_f32 v[128:129], v[192:193], v[196:197], v[128:129]
	v_pk_mul_f32 v[190:191], v[188:189], v[138:139] op_sel_hi:[0,1]
	v_pk_mul_f32 v[192:193], v[188:189], v[140:141] op_sel_hi:[0,1]
	v_cvt_f32_f16_e32 v194, v158
	v_cvt_f32_f16_sdwa v195, v158 dst_sel:DWORD dst_unused:UNUSED_PAD src0_sel:WORD_1
	v_cvt_f32_f16_e32 v196, v159
	v_cvt_f32_f16_sdwa v197, v159 dst_sel:DWORD dst_unused:UNUSED_PAD src0_sel:WORD_1
	v_pk_fma_f32 v[126:127], v[190:191], v[194:195], v[126:127]
	v_pk_fma_f32 v[128:129], v[192:193], v[196:197], v[128:129]
	v_mul_f32_e32 v190, 0xbfb8aa3b, v126
	v_mul_f32_e32 v191, 0xbfb8aa3b, v127
	v_mul_f32_e32 v192, 0xbfb8aa3b, v128
	v_mul_f32_e32 v193, 0xbfb8aa3b, v129
	v_exp_f32_e32 v190, v190
	v_exp_f32_e32 v191, v191
	v_exp_f32_e32 v192, v192
	v_exp_f32_e32 v193, v193
	v_add_f32_e32 v190, 1.0, v190
	v_add_f32_e32 v191, 1.0, v191
	v_add_f32_e32 v192, 1.0, v192
	v_add_f32_e32 v193, 1.0, v193
	v_rcp_f32_e32 v190, v190
	v_rcp_f32_e32 v191, v191
	v_rcp_f32_e32 v192, v192
	v_rcp_f32_e32 v193, v193
	s_nop 0
	v_pk_mul_f32 v[126:127], v[126:127], v[190:191]
	v_pk_mul_f32 v[128:129], v[128:129], v[192:193]
	v_pk_mul_f32 v[126:127], v[122:123], v[126:127]
	v_pk_mul_f32 v[128:129], v[124:125], v[128:129]
	v_cvt_pk_f16_f32 v126, v126, v127
	v_cvt_pk_f16_f32 v127, v128, v129
	global_store_dwordx2 v183, v[126:127], s[96:97]
	v_pk_mul_f32 v[118:119], v[118:119], v[146:147]
	v_pk_mul_f32 v[120:121], v[120:121], v[148:149]
	v_pk_mul_f32 v[190:191], v[186:187], v[142:143] op_sel_hi:[0,1]
	v_pk_mul_f32 v[192:193], v[186:187], v[144:145] op_sel_hi:[0,1]
	v_cvt_f32_f16_e32 v194, v156
	v_cvt_f32_f16_sdwa v195, v156 dst_sel:DWORD dst_unused:UNUSED_PAD src0_sel:WORD_1
	v_cvt_f32_f16_e32 v196, v157
	v_cvt_f32_f16_sdwa v197, v157 dst_sel:DWORD dst_unused:UNUSED_PAD src0_sel:WORD_1
	v_pk_fma_f32 v[118:119], v[190:191], v[194:195], v[118:119]
	v_pk_fma_f32 v[120:121], v[192:193], v[196:197], v[120:121]
	v_pk_mul_f32 v[190:191], v[188:189], v[150:151] op_sel_hi:[0,1]
	v_pk_mul_f32 v[192:193], v[188:189], v[152:153] op_sel_hi:[0,1]
	v_cvt_f32_f16_e32 v194, v160
	v_cvt_f32_f16_sdwa v195, v160 dst_sel:DWORD dst_unused:UNUSED_PAD src0_sel:WORD_1
	v_cvt_f32_f16_e32 v196, v161
	v_cvt_f32_f16_sdwa v197, v161 dst_sel:DWORD dst_unused:UNUSED_PAD src0_sel:WORD_1
	v_pk_fma_f32 v[118:119], v[190:191], v[194:195], v[118:119]
	v_pk_fma_f32 v[120:121], v[192:193], v[196:197], v[120:121]
	v_mul_f32_e32 v190, 0xbfb8aa3b, v118
	v_mul_f32_e32 v191, 0xbfb8aa3b, v119
	v_mul_f32_e32 v192, 0xbfb8aa3b, v120
	v_mul_f32_e32 v193, 0xbfb8aa3b, v121
	v_exp_f32_e32 v190, v190
	v_exp_f32_e32 v191, v191
	v_exp_f32_e32 v192, v192
	v_exp_f32_e32 v193, v193
	v_add_f32_e32 v190, 1.0, v190
	v_add_f32_e32 v191, 1.0, v191
	v_add_f32_e32 v192, 1.0, v192
	v_add_f32_e32 v193, 1.0, v193
	v_rcp_f32_e32 v190, v190
	v_rcp_f32_e32 v191, v191
	v_rcp_f32_e32 v192, v192
	v_rcp_f32_e32 v193, v193
	s_nop 0
	v_pk_mul_f32 v[118:119], v[118:119], v[190:191]
	v_pk_mul_f32 v[120:121], v[120:121], v[192:193]
	v_pk_mul_f32 v[118:119], v[114:115], v[118:119]
	v_pk_mul_f32 v[120:121], v[116:117], v[120:121]
	v_cvt_pk_f16_f32 v118, v118, v119
	v_cvt_pk_f16_f32 v119, v120, v121
	global_store_dwordx2 v183, v[118:119], s[96:97] offset:32
	s_mov_b64 exec, s[4:5]
	v_add_u32_e32 v179, 0x2200, v201
	ds_read2_b64 v[154:157], v179 offset1:4
	ds_read2_b64 v[158:161], v179 offset0:68 offset1:72
	v_add_u32_e32 v180, 16, v200
	v_add_u32_e32 v181, s34, v180
	v_add_u32_e32 v182, -1, v180
	v_cmp_gt_u32_e32 vcc, 0xfe, v182
	v_cmp_gt_i32_e64 s[2:3], s6, v181
	v_cmp_gt_i32_e64 s[4:5], s68, v181
	v_mad_u32_u24 v183, v181, s52, v207
	s_and_b64 s[2:3], vcc, s[2:3]
	v_cndmask_b32_e64 v184, v216, v217, s[4:5]
	v_and_b32_e32 v185, v184, v181
	v_cmp_eq_u32_e32 vcc, 0, v185
	s_nop 1
	v_cndmask_b32_e64 v186, 1.0, 0, vcc
	v_cmp_eq_u32_e32 vcc, v185, v184
	s_nop 1
	v_cndmask_b32_e64 v188, 1.0, 0, vcc
	s_and_saveexec_b64 s[4:5], s[2:3]
	s_waitcnt lgkmcnt(2)
	v_pk_mul_f32 v[110:111], v[110:111], v[134:135]
	v_pk_mul_f32 v[112:113], v[112:113], v[136:137]
	v_pk_mul_f32 v[190:191], v[186:187], v[130:131] op_sel_hi:[0,1]
	v_pk_mul_f32 v[192:193], v[186:187], v[132:133] op_sel_hi:[0,1]
	v_cvt_f32_f16_e32 v194, v162
	v_cvt_f32_f16_sdwa v195, v162 dst_sel:DWORD dst_unused:UNUSED_PAD src0_sel:WORD_1
	v_cvt_f32_f16_e32 v196, v163
	v_cvt_f32_f16_sdwa v197, v163 dst_sel:DWORD dst_unused:UNUSED_PAD src0_sel:WORD_1
	v_pk_fma_f32 v[110:111], v[190:191], v[194:195], v[110:111]
	v_pk_fma_f32 v[112:113], v[192:193], v[196:197], v[112:113]
	v_pk_mul_f32 v[190:191], v[188:189], v[138:139] op_sel_hi:[0,1]
	v_pk_mul_f32 v[192:193], v[188:189], v[140:141] op_sel_hi:[0,1]
	v_cvt_f32_f16_e32 v194, v166
	v_cvt_f32_f16_sdwa v195, v166 dst_sel:DWORD dst_unused:UNUSED_PAD src0_sel:WORD_1
	v_cvt_f32_f16_e32 v196, v167
	v_cvt_f32_f16_sdwa v197, v167 dst_sel:DWORD dst_unused:UNUSED_PAD src0_sel:WORD_1
	v_pk_fma_f32 v[110:111], v[190:191], v[194:195], v[110:111]
	v_pk_fma_f32 v[112:113], v[192:193], v[196:197], v[112:113]
	v_mul_f32_e32 v190, 0xbfb8aa3b, v110
	v_mul_f32_e32 v191, 0xbfb8aa3b, v111
	v_mul_f32_e32 v192, 0xbfb8aa3b, v112
	v_mul_f32_e32 v193, 0xbfb8aa3b, v113
	v_exp_f32_e32 v190, v190
	v_exp_f32_e32 v191, v191
	v_exp_f32_e32 v192, v192
	v_exp_f32_e32 v193, v193
	v_add_f32_e32 v190, 1.0, v190
	v_add_f32_e32 v191, 1.0, v191
	v_add_f32_e32 v192, 1.0, v192
	v_add_f32_e32 v193, 1.0, v193
	v_rcp_f32_e32 v190, v190
	v_rcp_f32_e32 v191, v191
	v_rcp_f32_e32 v192, v192
	v_rcp_f32_e32 v193, v193
	s_nop 0
	v_pk_mul_f32 v[110:111], v[110:111], v[190:191]
	v_pk_mul_f32 v[112:113], v[112:113], v[192:193]
	v_pk_mul_f32 v[110:111], v[106:107], v[110:111]
	v_pk_mul_f32 v[112:113], v[108:109], v[112:113]
	v_cvt_pk_f16_f32 v110, v110, v111
	v_cvt_pk_f16_f32 v111, v112, v113
	global_store_dwordx2 v183, v[110:111], s[96:97]
	v_pk_mul_f32 v[102:103], v[102:103], v[146:147]
	v_pk_mul_f32 v[104:105], v[104:105], v[148:149]
	v_pk_mul_f32 v[190:191], v[186:187], v[142:143] op_sel_hi:[0,1]
	v_pk_mul_f32 v[192:193], v[186:187], v[144:145] op_sel_hi:[0,1]
	v_cvt_f32_f16_e32 v194, v164
	v_cvt_f32_f16_sdwa v195, v164 dst_sel:DWORD dst_unused:UNUSED_PAD src0_sel:WORD_1
	v_cvt_f32_f16_e32 v196, v165
	v_cvt_f32_f16_sdwa v197, v165 dst_sel:DWORD dst_unused:UNUSED_PAD src0_sel:WORD_1
	v_pk_fma_f32 v[102:103], v[190:191], v[194:195], v[102:103]
	v_pk_fma_f32 v[104:105], v[192:193], v[196:197], v[104:105]
	v_pk_mul_f32 v[190:191], v[188:189], v[150:151] op_sel_hi:[0,1]
	v_pk_mul_f32 v[192:193], v[188:189], v[152:153] op_sel_hi:[0,1]
	v_cvt_f32_f16_e32 v194, v168
	v_cvt_f32_f16_sdwa v195, v168 dst_sel:DWORD dst_unused:UNUSED_PAD src0_sel:WORD_1
	v_cvt_f32_f16_e32 v196, v169
	v_cvt_f32_f16_sdwa v197, v169 dst_sel:DWORD dst_unused:UNUSED_PAD src0_sel:WORD_1
	v_pk_fma_f32 v[102:103], v[190:191], v[194:195], v[102:103]
	v_pk_fma_f32 v[104:105], v[192:193], v[196:197], v[104:105]
	v_mul_f32_e32 v190, 0xbfb8aa3b, v102
	v_mul_f32_e32 v191, 0xbfb8aa3b, v103
	v_mul_f32_e32 v192, 0xbfb8aa3b, v104
	v_mul_f32_e32 v193, 0xbfb8aa3b, v105
	v_exp_f32_e32 v190, v190
	v_exp_f32_e32 v191, v191
	v_exp_f32_e32 v192, v192
	v_exp_f32_e32 v193, v193
	v_add_f32_e32 v190, 1.0, v190
	v_add_f32_e32 v191, 1.0, v191
	v_add_f32_e32 v192, 1.0, v192
	v_add_f32_e32 v193, 1.0, v193
	v_rcp_f32_e32 v190, v190
	v_rcp_f32_e32 v191, v191
	v_rcp_f32_e32 v192, v192
	v_rcp_f32_e32 v193, v193
	s_nop 0
	v_pk_mul_f32 v[102:103], v[102:103], v[190:191]
	v_pk_mul_f32 v[104:105], v[104:105], v[192:193]
	v_pk_mul_f32 v[102:103], v[98:99], v[102:103]
	v_pk_mul_f32 v[104:105], v[100:101], v[104:105]
	v_cvt_pk_f16_f32 v102, v102, v103
	v_cvt_pk_f16_f32 v103, v104, v105
	global_store_dwordx2 v183, v[102:103], s[96:97] offset:32
	s_mov_b64 exec, s[4:5]
	v_add_u32_e32 v179, 0x3300, v201
	ds_read2_b64 v[162:165], v179 offset1:4
	ds_read2_b64 v[166:169], v179 offset0:68 offset1:72
	v_add_u32_e32 v180, 32, v200
	v_add_u32_e32 v181, s34, v180
	v_add_u32_e32 v182, -1, v180
	v_cmp_gt_u32_e32 vcc, 0xfe, v182
	v_cmp_gt_i32_e64 s[2:3], s6, v181
	v_cmp_gt_i32_e64 s[4:5], s68, v181
	v_mad_u32_u24 v183, v181, s52, v207
	s_and_b64 s[2:3], vcc, s[2:3]
	v_cndmask_b32_e64 v184, v216, v217, s[4:5]
	v_and_b32_e32 v185, v184, v181
	v_cmp_eq_u32_e32 vcc, 0, v185
	s_nop 1
	v_cndmask_b32_e64 v186, 1.0, 0, vcc
	v_cmp_eq_u32_e32 vcc, v185, v184
	s_nop 1
	v_cndmask_b32_e64 v188, 1.0, 0, vcc
	s_and_saveexec_b64 s[4:5], s[2:3]
	s_waitcnt lgkmcnt(2)
	v_pk_mul_f32 v[94:95], v[94:95], v[134:135]
	v_pk_mul_f32 v[96:97], v[96:97], v[136:137]
	v_pk_mul_f32 v[190:191], v[186:187], v[130:131] op_sel_hi:[0,1]
	v_pk_mul_f32 v[192:193], v[186:187], v[132:133] op_sel_hi:[0,1]
	v_cvt_f32_f16_e32 v194, v154
	v_cvt_f32_f16_sdwa v195, v154 dst_sel:DWORD dst_unused:UNUSED_PAD src0_sel:WORD_1
	v_cvt_f32_f16_e32 v196, v155
	v_cvt_f32_f16_sdwa v197, v155 dst_sel:DWORD dst_unused:UNUSED_PAD src0_sel:WORD_1
	v_pk_fma_f32 v[94:95], v[190:191], v[194:195], v[94:95]
	v_pk_fma_f32 v[96:97], v[192:193], v[196:197], v[96:97]
	v_pk_mul_f32 v[190:191], v[188:189], v[138:139] op_sel_hi:[0,1]
	v_pk_mul_f32 v[192:193], v[188:189], v[140:141] op_sel_hi:[0,1]
	v_cvt_f32_f16_e32 v194, v158
	v_cvt_f32_f16_sdwa v195, v158 dst_sel:DWORD dst_unused:UNUSED_PAD src0_sel:WORD_1
	v_cvt_f32_f16_e32 v196, v159
	v_cvt_f32_f16_sdwa v197, v159 dst_sel:DWORD dst_unused:UNUSED_PAD src0_sel:WORD_1
	v_pk_fma_f32 v[94:95], v[190:191], v[194:195], v[94:95]
	v_pk_fma_f32 v[96:97], v[192:193], v[196:197], v[96:97]
	v_mul_f32_e32 v190, 0xbfb8aa3b, v94
	v_mul_f32_e32 v191, 0xbfb8aa3b, v95
	v_mul_f32_e32 v192, 0xbfb8aa3b, v96
	v_mul_f32_e32 v193, 0xbfb8aa3b, v97
	v_exp_f32_e32 v190, v190
	v_exp_f32_e32 v191, v191
	v_exp_f32_e32 v192, v192
	v_exp_f32_e32 v193, v193
	v_add_f32_e32 v190, 1.0, v190
	v_add_f32_e32 v191, 1.0, v191
	v_add_f32_e32 v192, 1.0, v192
	v_add_f32_e32 v193, 1.0, v193
	v_rcp_f32_e32 v190, v190
	v_rcp_f32_e32 v191, v191
	v_rcp_f32_e32 v192, v192
	v_rcp_f32_e32 v193, v193
	s_nop 0
	v_pk_mul_f32 v[94:95], v[94:95], v[190:191]
	v_pk_mul_f32 v[96:97], v[96:97], v[192:193]
	v_pk_mul_f32 v[94:95], v[90:91], v[94:95]
	v_pk_mul_f32 v[96:97], v[92:93], v[96:97]
	v_cvt_pk_f16_f32 v94, v94, v95
	v_cvt_pk_f16_f32 v95, v96, v97
	global_store_dwordx2 v183, v[94:95], s[96:97]
	v_pk_mul_f32 v[86:87], v[86:87], v[146:147]
	v_pk_mul_f32 v[88:89], v[88:89], v[148:149]
	v_pk_mul_f32 v[190:191], v[186:187], v[142:143] op_sel_hi:[0,1]
	v_pk_mul_f32 v[192:193], v[186:187], v[144:145] op_sel_hi:[0,1]
	v_cvt_f32_f16_e32 v194, v156
	v_cvt_f32_f16_sdwa v195, v156 dst_sel:DWORD dst_unused:UNUSED_PAD src0_sel:WORD_1
	v_cvt_f32_f16_e32 v196, v157
	v_cvt_f32_f16_sdwa v197, v157 dst_sel:DWORD dst_unused:UNUSED_PAD src0_sel:WORD_1
	v_pk_fma_f32 v[86:87], v[190:191], v[194:195], v[86:87]
	v_pk_fma_f32 v[88:89], v[192:193], v[196:197], v[88:89]
	v_pk_mul_f32 v[190:191], v[188:189], v[150:151] op_sel_hi:[0,1]
	v_pk_mul_f32 v[192:193], v[188:189], v[152:153] op_sel_hi:[0,1]
	v_cvt_f32_f16_e32 v194, v160
	v_cvt_f32_f16_sdwa v195, v160 dst_sel:DWORD dst_unused:UNUSED_PAD src0_sel:WORD_1
	v_cvt_f32_f16_e32 v196, v161
	v_cvt_f32_f16_sdwa v197, v161 dst_sel:DWORD dst_unused:UNUSED_PAD src0_sel:WORD_1
	v_pk_fma_f32 v[86:87], v[190:191], v[194:195], v[86:87]
	v_pk_fma_f32 v[88:89], v[192:193], v[196:197], v[88:89]
	v_mul_f32_e32 v190, 0xbfb8aa3b, v86
	v_mul_f32_e32 v191, 0xbfb8aa3b, v87
	v_mul_f32_e32 v192, 0xbfb8aa3b, v88
	v_mul_f32_e32 v193, 0xbfb8aa3b, v89
	v_exp_f32_e32 v190, v190
	v_exp_f32_e32 v191, v191
	v_exp_f32_e32 v192, v192
	v_exp_f32_e32 v193, v193
	v_add_f32_e32 v190, 1.0, v190
	v_add_f32_e32 v191, 1.0, v191
	v_add_f32_e32 v192, 1.0, v192
	v_add_f32_e32 v193, 1.0, v193
	v_rcp_f32_e32 v190, v190
	v_rcp_f32_e32 v191, v191
	v_rcp_f32_e32 v192, v192
	v_rcp_f32_e32 v193, v193
	s_nop 0
	v_pk_mul_f32 v[86:87], v[86:87], v[190:191]
	v_pk_mul_f32 v[88:89], v[88:89], v[192:193]
	v_pk_mul_f32 v[86:87], v[82:83], v[86:87]
	v_pk_mul_f32 v[88:89], v[84:85], v[88:89]
	v_cvt_pk_f16_f32 v86, v86, v87
	v_cvt_pk_f16_f32 v87, v88, v89
	global_store_dwordx2 v183, v[86:87], s[96:97] offset:32
	s_mov_b64 exec, s[4:5]
	v_add_u32_e32 v179, 0x4400, v201
	ds_read2_b64 v[154:157], v179 offset1:4
	ds_read2_b64 v[158:161], v179 offset0:68 offset1:72
	v_add_u32_e32 v180, 48, v200
	v_add_u32_e32 v181, s34, v180
	v_add_u32_e32 v182, -1, v180
	v_cmp_gt_u32_e32 vcc, 0xfe, v182
	v_cmp_gt_i32_e64 s[2:3], s6, v181
	v_cmp_gt_i32_e64 s[4:5], s68, v181
	v_mad_u32_u24 v183, v181, s52, v207
	s_and_b64 s[2:3], vcc, s[2:3]
	v_cndmask_b32_e64 v184, v216, v217, s[4:5]
	v_and_b32_e32 v185, v184, v181
	v_cmp_eq_u32_e32 vcc, 0, v185
	s_nop 1
	v_cndmask_b32_e64 v186, 1.0, 0, vcc
	v_cmp_eq_u32_e32 vcc, v185, v184
	s_nop 1
	v_cndmask_b32_e64 v188, 1.0, 0, vcc
	s_and_saveexec_b64 s[4:5], s[2:3]
	s_waitcnt lgkmcnt(2)
	v_pk_mul_f32 v[78:79], v[78:79], v[134:135]
	v_pk_mul_f32 v[80:81], v[80:81], v[136:137]
	v_pk_mul_f32 v[190:191], v[186:187], v[130:131] op_sel_hi:[0,1]
	v_pk_mul_f32 v[192:193], v[186:187], v[132:133] op_sel_hi:[0,1]
	v_cvt_f32_f16_e32 v194, v162
	v_cvt_f32_f16_sdwa v195, v162 dst_sel:DWORD dst_unused:UNUSED_PAD src0_sel:WORD_1
	v_cvt_f32_f16_e32 v196, v163
	v_cvt_f32_f16_sdwa v197, v163 dst_sel:DWORD dst_unused:UNUSED_PAD src0_sel:WORD_1
	v_pk_fma_f32 v[78:79], v[190:191], v[194:195], v[78:79]
	v_pk_fma_f32 v[80:81], v[192:193], v[196:197], v[80:81]
	v_pk_mul_f32 v[190:191], v[188:189], v[138:139] op_sel_hi:[0,1]
	v_pk_mul_f32 v[192:193], v[188:189], v[140:141] op_sel_hi:[0,1]
	v_cvt_f32_f16_e32 v194, v166
	v_cvt_f32_f16_sdwa v195, v166 dst_sel:DWORD dst_unused:UNUSED_PAD src0_sel:WORD_1
	v_cvt_f32_f16_e32 v196, v167
	v_cvt_f32_f16_sdwa v197, v167 dst_sel:DWORD dst_unused:UNUSED_PAD src0_sel:WORD_1
	v_pk_fma_f32 v[78:79], v[190:191], v[194:195], v[78:79]
	v_pk_fma_f32 v[80:81], v[192:193], v[196:197], v[80:81]
	v_mul_f32_e32 v190, 0xbfb8aa3b, v78
	v_mul_f32_e32 v191, 0xbfb8aa3b, v79
	v_mul_f32_e32 v192, 0xbfb8aa3b, v80
	v_mul_f32_e32 v193, 0xbfb8aa3b, v81
	v_exp_f32_e32 v190, v190
	v_exp_f32_e32 v191, v191
	v_exp_f32_e32 v192, v192
	v_exp_f32_e32 v193, v193
	v_add_f32_e32 v190, 1.0, v190
	v_add_f32_e32 v191, 1.0, v191
	v_add_f32_e32 v192, 1.0, v192
	v_add_f32_e32 v193, 1.0, v193
	v_rcp_f32_e32 v190, v190
	v_rcp_f32_e32 v191, v191
	v_rcp_f32_e32 v192, v192
	v_rcp_f32_e32 v193, v193
	s_nop 0
	v_pk_mul_f32 v[78:79], v[78:79], v[190:191]
	v_pk_mul_f32 v[80:81], v[80:81], v[192:193]
	v_pk_mul_f32 v[78:79], v[74:75], v[78:79]
	v_pk_mul_f32 v[80:81], v[76:77], v[80:81]
	v_cvt_pk_f16_f32 v78, v78, v79
	v_cvt_pk_f16_f32 v79, v80, v81
	global_store_dwordx2 v183, v[78:79], s[96:97]
	v_pk_mul_f32 v[70:71], v[70:71], v[146:147]
	v_pk_mul_f32 v[72:73], v[72:73], v[148:149]
	v_pk_mul_f32 v[190:191], v[186:187], v[142:143] op_sel_hi:[0,1]
	v_pk_mul_f32 v[192:193], v[186:187], v[144:145] op_sel_hi:[0,1]
	v_cvt_f32_f16_e32 v194, v164
	v_cvt_f32_f16_sdwa v195, v164 dst_sel:DWORD dst_unused:UNUSED_PAD src0_sel:WORD_1
	v_cvt_f32_f16_e32 v196, v165
	v_cvt_f32_f16_sdwa v197, v165 dst_sel:DWORD dst_unused:UNUSED_PAD src0_sel:WORD_1
	v_pk_fma_f32 v[70:71], v[190:191], v[194:195], v[70:71]
	v_pk_fma_f32 v[72:73], v[192:193], v[196:197], v[72:73]
	v_pk_mul_f32 v[190:191], v[188:189], v[150:151] op_sel_hi:[0,1]
	v_pk_mul_f32 v[192:193], v[188:189], v[152:153] op_sel_hi:[0,1]
	v_cvt_f32_f16_e32 v194, v168
	v_cvt_f32_f16_sdwa v195, v168 dst_sel:DWORD dst_unused:UNUSED_PAD src0_sel:WORD_1
	v_cvt_f32_f16_e32 v196, v169
	v_cvt_f32_f16_sdwa v197, v169 dst_sel:DWORD dst_unused:UNUSED_PAD src0_sel:WORD_1
	v_pk_fma_f32 v[70:71], v[190:191], v[194:195], v[70:71]
	v_pk_fma_f32 v[72:73], v[192:193], v[196:197], v[72:73]
	v_mul_f32_e32 v190, 0xbfb8aa3b, v70
	v_mul_f32_e32 v191, 0xbfb8aa3b, v71
	v_mul_f32_e32 v192, 0xbfb8aa3b, v72
	v_mul_f32_e32 v193, 0xbfb8aa3b, v73
	v_exp_f32_e32 v190, v190
	v_exp_f32_e32 v191, v191
	v_exp_f32_e32 v192, v192
	v_exp_f32_e32 v193, v193
	v_add_f32_e32 v190, 1.0, v190
	v_add_f32_e32 v191, 1.0, v191
	v_add_f32_e32 v192, 1.0, v192
	v_add_f32_e32 v193, 1.0, v193
	v_rcp_f32_e32 v190, v190
	v_rcp_f32_e32 v191, v191
	v_rcp_f32_e32 v192, v192
	v_rcp_f32_e32 v193, v193
	s_nop 0
	v_pk_mul_f32 v[70:71], v[70:71], v[190:191]
	v_pk_mul_f32 v[72:73], v[72:73], v[192:193]
	v_pk_mul_f32 v[70:71], v[66:67], v[70:71]
	v_pk_mul_f32 v[72:73], v[68:69], v[72:73]
	v_cvt_pk_f16_f32 v70, v70, v71
	v_cvt_pk_f16_f32 v71, v72, v73
	global_store_dwordx2 v183, v[70:71], s[96:97] offset:32
	s_mov_b64 exec, s[4:5]
	v_add_u32_e32 v179, 0x5500, v201
	ds_read2_b64 v[162:165], v179 offset1:4
	ds_read2_b64 v[166:169], v179 offset0:68 offset1:72
	v_add_u32_e32 v180, 64, v200
	v_add_u32_e32 v181, s34, v180
	v_add_u32_e32 v182, -1, v180
	v_cmp_gt_u32_e32 vcc, 0xfe, v182
	v_cmp_gt_i32_e64 s[2:3], s6, v181
	v_cmp_gt_i32_e64 s[4:5], s68, v181
	v_mad_u32_u24 v183, v181, s52, v207
	s_and_b64 s[2:3], vcc, s[2:3]
	v_cndmask_b32_e64 v184, v216, v217, s[4:5]
	v_and_b32_e32 v185, v184, v181
	v_cmp_eq_u32_e32 vcc, 0, v185
	s_nop 1
	v_cndmask_b32_e64 v186, 1.0, 0, vcc
	v_cmp_eq_u32_e32 vcc, v185, v184
	s_nop 1
	v_cndmask_b32_e64 v188, 1.0, 0, vcc
	s_and_saveexec_b64 s[4:5], s[2:3]
	s_waitcnt lgkmcnt(2)
	v_pk_mul_f32 v[62:63], v[62:63], v[134:135]
	v_pk_mul_f32 v[64:65], v[64:65], v[136:137]
	v_pk_mul_f32 v[190:191], v[186:187], v[130:131] op_sel_hi:[0,1]
	v_pk_mul_f32 v[192:193], v[186:187], v[132:133] op_sel_hi:[0,1]
	v_cvt_f32_f16_e32 v194, v154
	v_cvt_f32_f16_sdwa v195, v154 dst_sel:DWORD dst_unused:UNUSED_PAD src0_sel:WORD_1
	v_cvt_f32_f16_e32 v196, v155
	v_cvt_f32_f16_sdwa v197, v155 dst_sel:DWORD dst_unused:UNUSED_PAD src0_sel:WORD_1
	v_pk_fma_f32 v[62:63], v[190:191], v[194:195], v[62:63]
	v_pk_fma_f32 v[64:65], v[192:193], v[196:197], v[64:65]
	v_pk_mul_f32 v[190:191], v[188:189], v[138:139] op_sel_hi:[0,1]
	v_pk_mul_f32 v[192:193], v[188:189], v[140:141] op_sel_hi:[0,1]
	v_cvt_f32_f16_e32 v194, v158
	v_cvt_f32_f16_sdwa v195, v158 dst_sel:DWORD dst_unused:UNUSED_PAD src0_sel:WORD_1
	v_cvt_f32_f16_e32 v196, v159
	v_cvt_f32_f16_sdwa v197, v159 dst_sel:DWORD dst_unused:UNUSED_PAD src0_sel:WORD_1
	v_pk_fma_f32 v[62:63], v[190:191], v[194:195], v[62:63]
	v_pk_fma_f32 v[64:65], v[192:193], v[196:197], v[64:65]
	v_mul_f32_e32 v190, 0xbfb8aa3b, v62
	v_mul_f32_e32 v191, 0xbfb8aa3b, v63
	v_mul_f32_e32 v192, 0xbfb8aa3b, v64
	v_mul_f32_e32 v193, 0xbfb8aa3b, v65
	v_exp_f32_e32 v190, v190
	v_exp_f32_e32 v191, v191
	v_exp_f32_e32 v192, v192
	v_exp_f32_e32 v193, v193
	v_add_f32_e32 v190, 1.0, v190
	v_add_f32_e32 v191, 1.0, v191
	v_add_f32_e32 v192, 1.0, v192
	v_add_f32_e32 v193, 1.0, v193
	v_rcp_f32_e32 v190, v190
	v_rcp_f32_e32 v191, v191
	v_rcp_f32_e32 v192, v192
	v_rcp_f32_e32 v193, v193
	s_nop 0
	v_pk_mul_f32 v[62:63], v[62:63], v[190:191]
	v_pk_mul_f32 v[64:65], v[64:65], v[192:193]
	v_pk_mul_f32 v[62:63], v[58:59], v[62:63]
	v_pk_mul_f32 v[64:65], v[60:61], v[64:65]
	v_cvt_pk_f16_f32 v62, v62, v63
	v_cvt_pk_f16_f32 v63, v64, v65
	global_store_dwordx2 v183, v[62:63], s[96:97]
	v_pk_mul_f32 v[54:55], v[54:55], v[146:147]
	v_pk_mul_f32 v[56:57], v[56:57], v[148:149]
	v_pk_mul_f32 v[190:191], v[186:187], v[142:143] op_sel_hi:[0,1]
	v_pk_mul_f32 v[192:193], v[186:187], v[144:145] op_sel_hi:[0,1]
	v_cvt_f32_f16_e32 v194, v156
	v_cvt_f32_f16_sdwa v195, v156 dst_sel:DWORD dst_unused:UNUSED_PAD src0_sel:WORD_1
	v_cvt_f32_f16_e32 v196, v157
	v_cvt_f32_f16_sdwa v197, v157 dst_sel:DWORD dst_unused:UNUSED_PAD src0_sel:WORD_1
	v_pk_fma_f32 v[54:55], v[190:191], v[194:195], v[54:55]
	v_pk_fma_f32 v[56:57], v[192:193], v[196:197], v[56:57]
	v_pk_mul_f32 v[190:191], v[188:189], v[150:151] op_sel_hi:[0,1]
	v_pk_mul_f32 v[192:193], v[188:189], v[152:153] op_sel_hi:[0,1]
	v_cvt_f32_f16_e32 v194, v160
	v_cvt_f32_f16_sdwa v195, v160 dst_sel:DWORD dst_unused:UNUSED_PAD src0_sel:WORD_1
	v_cvt_f32_f16_e32 v196, v161
	v_cvt_f32_f16_sdwa v197, v161 dst_sel:DWORD dst_unused:UNUSED_PAD src0_sel:WORD_1
	v_pk_fma_f32 v[54:55], v[190:191], v[194:195], v[54:55]
	v_pk_fma_f32 v[56:57], v[192:193], v[196:197], v[56:57]
	v_mul_f32_e32 v190, 0xbfb8aa3b, v54
	v_mul_f32_e32 v191, 0xbfb8aa3b, v55
	v_mul_f32_e32 v192, 0xbfb8aa3b, v56
	v_mul_f32_e32 v193, 0xbfb8aa3b, v57
	v_exp_f32_e32 v190, v190
	v_exp_f32_e32 v191, v191
	v_exp_f32_e32 v192, v192
	v_exp_f32_e32 v193, v193
	v_add_f32_e32 v190, 1.0, v190
	v_add_f32_e32 v191, 1.0, v191
	v_add_f32_e32 v192, 1.0, v192
	v_add_f32_e32 v193, 1.0, v193
	v_rcp_f32_e32 v190, v190
	v_rcp_f32_e32 v191, v191
	v_rcp_f32_e32 v192, v192
	v_rcp_f32_e32 v193, v193
	s_nop 0
	v_pk_mul_f32 v[54:55], v[54:55], v[190:191]
	v_pk_mul_f32 v[56:57], v[56:57], v[192:193]
	v_pk_mul_f32 v[54:55], v[50:51], v[54:55]
	v_pk_mul_f32 v[56:57], v[52:53], v[56:57]
	v_cvt_pk_f16_f32 v54, v54, v55
	v_cvt_pk_f16_f32 v55, v56, v57
	global_store_dwordx2 v183, v[54:55], s[96:97] offset:32
	s_mov_b64 exec, s[4:5]
	v_add_u32_e32 v179, 0x6600, v201
	ds_read2_b64 v[154:157], v179 offset1:4
	ds_read2_b64 v[158:161], v179 offset0:68 offset1:72
	v_add_u32_e32 v180, 80, v200
	v_add_u32_e32 v181, s34, v180
	v_add_u32_e32 v182, -1, v180
	v_cmp_gt_u32_e32 vcc, 0xfe, v182
	v_cmp_gt_i32_e64 s[2:3], s6, v181
	v_cmp_gt_i32_e64 s[4:5], s68, v181
	v_mad_u32_u24 v183, v181, s52, v207
	s_and_b64 s[2:3], vcc, s[2:3]
	v_cndmask_b32_e64 v184, v216, v217, s[4:5]
	v_and_b32_e32 v185, v184, v181
	v_cmp_eq_u32_e32 vcc, 0, v185
	s_nop 1
	v_cndmask_b32_e64 v186, 1.0, 0, vcc
	v_cmp_eq_u32_e32 vcc, v185, v184
	s_nop 1
	v_cndmask_b32_e64 v188, 1.0, 0, vcc
	s_and_saveexec_b64 s[4:5], s[2:3]
	s_waitcnt lgkmcnt(2)
	v_pk_mul_f32 v[46:47], v[46:47], v[134:135]
	v_pk_mul_f32 v[48:49], v[48:49], v[136:137]
	v_pk_mul_f32 v[190:191], v[186:187], v[130:131] op_sel_hi:[0,1]
	v_pk_mul_f32 v[192:193], v[186:187], v[132:133] op_sel_hi:[0,1]
	v_cvt_f32_f16_e32 v194, v162
	v_cvt_f32_f16_sdwa v195, v162 dst_sel:DWORD dst_unused:UNUSED_PAD src0_sel:WORD_1
	v_cvt_f32_f16_e32 v196, v163
	v_cvt_f32_f16_sdwa v197, v163 dst_sel:DWORD dst_unused:UNUSED_PAD src0_sel:WORD_1
	v_pk_fma_f32 v[46:47], v[190:191], v[194:195], v[46:47]
	v_pk_fma_f32 v[48:49], v[192:193], v[196:197], v[48:49]
	v_pk_mul_f32 v[190:191], v[188:189], v[138:139] op_sel_hi:[0,1]
	v_pk_mul_f32 v[192:193], v[188:189], v[140:141] op_sel_hi:[0,1]
	v_cvt_f32_f16_e32 v194, v166
	v_cvt_f32_f16_sdwa v195, v166 dst_sel:DWORD dst_unused:UNUSED_PAD src0_sel:WORD_1
	v_cvt_f32_f16_e32 v196, v167
	v_cvt_f32_f16_sdwa v197, v167 dst_sel:DWORD dst_unused:UNUSED_PAD src0_sel:WORD_1
	v_pk_fma_f32 v[46:47], v[190:191], v[194:195], v[46:47]
	v_pk_fma_f32 v[48:49], v[192:193], v[196:197], v[48:49]
	v_mul_f32_e32 v190, 0xbfb8aa3b, v46
	v_mul_f32_e32 v191, 0xbfb8aa3b, v47
	v_mul_f32_e32 v192, 0xbfb8aa3b, v48
	v_mul_f32_e32 v193, 0xbfb8aa3b, v49
	v_exp_f32_e32 v190, v190
	v_exp_f32_e32 v191, v191
	v_exp_f32_e32 v192, v192
	v_exp_f32_e32 v193, v193
	v_add_f32_e32 v190, 1.0, v190
	v_add_f32_e32 v191, 1.0, v191
	v_add_f32_e32 v192, 1.0, v192
	v_add_f32_e32 v193, 1.0, v193
	v_rcp_f32_e32 v190, v190
	v_rcp_f32_e32 v191, v191
	v_rcp_f32_e32 v192, v192
	v_rcp_f32_e32 v193, v193
	s_nop 0
	v_pk_mul_f32 v[46:47], v[46:47], v[190:191]
	v_pk_mul_f32 v[48:49], v[48:49], v[192:193]
	v_pk_mul_f32 v[46:47], v[42:43], v[46:47]
	v_pk_mul_f32 v[48:49], v[44:45], v[48:49]
	v_cvt_pk_f16_f32 v46, v46, v47
	v_cvt_pk_f16_f32 v47, v48, v49
	global_store_dwordx2 v183, v[46:47], s[96:97]
	v_pk_mul_f32 v[38:39], v[38:39], v[146:147]
	v_pk_mul_f32 v[40:41], v[40:41], v[148:149]
	v_pk_mul_f32 v[190:191], v[186:187], v[142:143] op_sel_hi:[0,1]
	v_pk_mul_f32 v[192:193], v[186:187], v[144:145] op_sel_hi:[0,1]
	v_cvt_f32_f16_e32 v194, v164
	v_cvt_f32_f16_sdwa v195, v164 dst_sel:DWORD dst_unused:UNUSED_PAD src0_sel:WORD_1
	v_cvt_f32_f16_e32 v196, v165
	v_cvt_f32_f16_sdwa v197, v165 dst_sel:DWORD dst_unused:UNUSED_PAD src0_sel:WORD_1
	v_pk_fma_f32 v[38:39], v[190:191], v[194:195], v[38:39]
	v_pk_fma_f32 v[40:41], v[192:193], v[196:197], v[40:41]
	v_pk_mul_f32 v[190:191], v[188:189], v[150:151] op_sel_hi:[0,1]
	v_pk_mul_f32 v[192:193], v[188:189], v[152:153] op_sel_hi:[0,1]
	v_cvt_f32_f16_e32 v194, v168
	v_cvt_f32_f16_sdwa v195, v168 dst_sel:DWORD dst_unused:UNUSED_PAD src0_sel:WORD_1
	v_cvt_f32_f16_e32 v196, v169
	v_cvt_f32_f16_sdwa v197, v169 dst_sel:DWORD dst_unused:UNUSED_PAD src0_sel:WORD_1
	v_pk_fma_f32 v[38:39], v[190:191], v[194:195], v[38:39]
	v_pk_fma_f32 v[40:41], v[192:193], v[196:197], v[40:41]
	v_mul_f32_e32 v190, 0xbfb8aa3b, v38
	v_mul_f32_e32 v191, 0xbfb8aa3b, v39
	v_mul_f32_e32 v192, 0xbfb8aa3b, v40
	v_mul_f32_e32 v193, 0xbfb8aa3b, v41
	v_exp_f32_e32 v190, v190
	v_exp_f32_e32 v191, v191
	v_exp_f32_e32 v192, v192
	v_exp_f32_e32 v193, v193
	v_add_f32_e32 v190, 1.0, v190
	v_add_f32_e32 v191, 1.0, v191
	v_add_f32_e32 v192, 1.0, v192
	v_add_f32_e32 v193, 1.0, v193
	v_rcp_f32_e32 v190, v190
	v_rcp_f32_e32 v191, v191
	v_rcp_f32_e32 v192, v192
	v_rcp_f32_e32 v193, v193
	s_nop 0
	v_pk_mul_f32 v[38:39], v[38:39], v[190:191]
	v_pk_mul_f32 v[40:41], v[40:41], v[192:193]
	v_pk_mul_f32 v[38:39], v[34:35], v[38:39]
	v_pk_mul_f32 v[40:41], v[36:37], v[40:41]
	v_cvt_pk_f16_f32 v38, v38, v39
	v_cvt_pk_f16_f32 v39, v40, v41
	global_store_dwordx2 v183, v[38:39], s[96:97] offset:32
	s_mov_b64 exec, s[4:5]
	v_add_u32_e32 v179, 0x7700, v201
	ds_read2_b64 v[162:165], v179 offset1:4
	ds_read2_b64 v[166:169], v179 offset0:68 offset1:72
	v_add_u32_e32 v180, 96, v200
	v_add_u32_e32 v181, s34, v180
	v_add_u32_e32 v182, -1, v180
	v_cmp_gt_u32_e32 vcc, 0xfe, v182
	v_cmp_gt_i32_e64 s[2:3], s6, v181
	v_cmp_gt_i32_e64 s[4:5], s68, v181
	v_mad_u32_u24 v183, v181, s52, v207
	s_and_b64 s[2:3], vcc, s[2:3]
	v_cndmask_b32_e64 v184, v216, v217, s[4:5]
	v_and_b32_e32 v185, v184, v181
	v_cmp_eq_u32_e32 vcc, 0, v185
	s_nop 1
	v_cndmask_b32_e64 v186, 1.0, 0, vcc
	v_cmp_eq_u32_e32 vcc, v185, v184
	s_nop 1
	v_cndmask_b32_e64 v188, 1.0, 0, vcc
	s_and_saveexec_b64 s[4:5], s[2:3]
	s_waitcnt lgkmcnt(2)
	v_pk_mul_f32 v[30:31], v[30:31], v[134:135]
	v_pk_mul_f32 v[32:33], v[32:33], v[136:137]
	v_pk_mul_f32 v[190:191], v[186:187], v[130:131] op_sel_hi:[0,1]
	v_pk_mul_f32 v[192:193], v[186:187], v[132:133] op_sel_hi:[0,1]
	v_cvt_f32_f16_e32 v194, v154
	v_cvt_f32_f16_sdwa v195, v154 dst_sel:DWORD dst_unused:UNUSED_PAD src0_sel:WORD_1
	v_cvt_f32_f16_e32 v196, v155
	v_cvt_f32_f16_sdwa v197, v155 dst_sel:DWORD dst_unused:UNUSED_PAD src0_sel:WORD_1
	v_pk_fma_f32 v[30:31], v[190:191], v[194:195], v[30:31]
	v_pk_fma_f32 v[32:33], v[192:193], v[196:197], v[32:33]
	v_pk_mul_f32 v[190:191], v[188:189], v[138:139] op_sel_hi:[0,1]
	v_pk_mul_f32 v[192:193], v[188:189], v[140:141] op_sel_hi:[0,1]
	v_cvt_f32_f16_e32 v194, v158
	v_cvt_f32_f16_sdwa v195, v158 dst_sel:DWORD dst_unused:UNUSED_PAD src0_sel:WORD_1
	v_cvt_f32_f16_e32 v196, v159
	v_cvt_f32_f16_sdwa v197, v159 dst_sel:DWORD dst_unused:UNUSED_PAD src0_sel:WORD_1
	v_pk_fma_f32 v[30:31], v[190:191], v[194:195], v[30:31]
	v_pk_fma_f32 v[32:33], v[192:193], v[196:197], v[32:33]
	v_mul_f32_e32 v190, 0xbfb8aa3b, v30
	v_mul_f32_e32 v191, 0xbfb8aa3b, v31
	v_mul_f32_e32 v192, 0xbfb8aa3b, v32
	v_mul_f32_e32 v193, 0xbfb8aa3b, v33
	v_exp_f32_e32 v190, v190
	v_exp_f32_e32 v191, v191
	v_exp_f32_e32 v192, v192
	v_exp_f32_e32 v193, v193
	v_add_f32_e32 v190, 1.0, v190
	v_add_f32_e32 v191, 1.0, v191
	v_add_f32_e32 v192, 1.0, v192
	v_add_f32_e32 v193, 1.0, v193
	v_rcp_f32_e32 v190, v190
	v_rcp_f32_e32 v191, v191
	v_rcp_f32_e32 v192, v192
	v_rcp_f32_e32 v193, v193
	s_nop 0
	v_pk_mul_f32 v[30:31], v[30:31], v[190:191]
	v_pk_mul_f32 v[32:33], v[32:33], v[192:193]
	v_pk_mul_f32 v[30:31], v[26:27], v[30:31]
	v_pk_mul_f32 v[32:33], v[28:29], v[32:33]
	v_cvt_pk_f16_f32 v30, v30, v31
	v_cvt_pk_f16_f32 v31, v32, v33
	global_store_dwordx2 v183, v[30:31], s[96:97]
	v_pk_mul_f32 v[22:23], v[22:23], v[146:147]
	v_pk_mul_f32 v[24:25], v[24:25], v[148:149]
	v_pk_mul_f32 v[190:191], v[186:187], v[142:143] op_sel_hi:[0,1]
	v_pk_mul_f32 v[192:193], v[186:187], v[144:145] op_sel_hi:[0,1]
	v_cvt_f32_f16_e32 v194, v156
	v_cvt_f32_f16_sdwa v195, v156 dst_sel:DWORD dst_unused:UNUSED_PAD src0_sel:WORD_1
	v_cvt_f32_f16_e32 v196, v157
	v_cvt_f32_f16_sdwa v197, v157 dst_sel:DWORD dst_unused:UNUSED_PAD src0_sel:WORD_1
	v_pk_fma_f32 v[22:23], v[190:191], v[194:195], v[22:23]
	v_pk_fma_f32 v[24:25], v[192:193], v[196:197], v[24:25]
	v_pk_mul_f32 v[190:191], v[188:189], v[150:151] op_sel_hi:[0,1]
	v_pk_mul_f32 v[192:193], v[188:189], v[152:153] op_sel_hi:[0,1]
	v_cvt_f32_f16_e32 v194, v160
	v_cvt_f32_f16_sdwa v195, v160 dst_sel:DWORD dst_unused:UNUSED_PAD src0_sel:WORD_1
	v_cvt_f32_f16_e32 v196, v161
	v_cvt_f32_f16_sdwa v197, v161 dst_sel:DWORD dst_unused:UNUSED_PAD src0_sel:WORD_1
	v_pk_fma_f32 v[22:23], v[190:191], v[194:195], v[22:23]
	v_pk_fma_f32 v[24:25], v[192:193], v[196:197], v[24:25]
	v_mul_f32_e32 v190, 0xbfb8aa3b, v22
	v_mul_f32_e32 v191, 0xbfb8aa3b, v23
	v_mul_f32_e32 v192, 0xbfb8aa3b, v24
	v_mul_f32_e32 v193, 0xbfb8aa3b, v25
	v_exp_f32_e32 v190, v190
	v_exp_f32_e32 v191, v191
	v_exp_f32_e32 v192, v192
	v_exp_f32_e32 v193, v193
	v_add_f32_e32 v190, 1.0, v190
	v_add_f32_e32 v191, 1.0, v191
	v_add_f32_e32 v192, 1.0, v192
	v_add_f32_e32 v193, 1.0, v193
	v_rcp_f32_e32 v190, v190
	v_rcp_f32_e32 v191, v191
	v_rcp_f32_e32 v192, v192
	v_rcp_f32_e32 v193, v193
	s_nop 0
	v_pk_mul_f32 v[22:23], v[22:23], v[190:191]
	v_pk_mul_f32 v[24:25], v[24:25], v[192:193]
	v_pk_mul_f32 v[22:23], v[18:19], v[22:23]
	v_pk_mul_f32 v[24:25], v[20:21], v[24:25]
	v_cvt_pk_f16_f32 v22, v22, v23
	v_cvt_pk_f16_f32 v23, v24, v25
	global_store_dwordx2 v183, v[22:23], s[96:97] offset:32
	s_mov_b64 exec, s[4:5]
	v_add_u32_e32 v180, 112, v200
	v_add_u32_e32 v181, s34, v180
	v_add_u32_e32 v182, -1, v180
	v_cmp_gt_u32_e32 vcc, 0xfe, v182
	v_cmp_gt_i32_e64 s[2:3], s6, v181
	v_cmp_gt_i32_e64 s[4:5], s68, v181
	v_mad_u32_u24 v183, v181, s52, v207
	s_and_b64 s[2:3], vcc, s[2:3]
	v_cndmask_b32_e64 v184, v216, v217, s[4:5]
	v_and_b32_e32 v185, v184, v181
	v_cmp_eq_u32_e32 vcc, 0, v185
	s_nop 1
	v_cndmask_b32_e64 v186, 1.0, 0, vcc
	v_cmp_eq_u32_e32 vcc, v185, v184
	s_nop 1
	v_cndmask_b32_e64 v188, 1.0, 0, vcc
	s_and_saveexec_b64 s[4:5], s[2:3]
	s_waitcnt lgkmcnt(0)
	v_pk_mul_f32 v[14:15], v[14:15], v[134:135]
	v_pk_mul_f32 v[16:17], v[16:17], v[136:137]
	v_pk_mul_f32 v[190:191], v[186:187], v[130:131] op_sel_hi:[0,1]
	v_pk_mul_f32 v[192:193], v[186:187], v[132:133] op_sel_hi:[0,1]
	v_cvt_f32_f16_e32 v194, v162
	v_cvt_f32_f16_sdwa v195, v162 dst_sel:DWORD dst_unused:UNUSED_PAD src0_sel:WORD_1
	v_cvt_f32_f16_e32 v196, v163
	v_cvt_f32_f16_sdwa v197, v163 dst_sel:DWORD dst_unused:UNUSED_PAD src0_sel:WORD_1
	v_pk_fma_f32 v[14:15], v[190:191], v[194:195], v[14:15]
	v_pk_fma_f32 v[16:17], v[192:193], v[196:197], v[16:17]
	v_pk_mul_f32 v[190:191], v[188:189], v[138:139] op_sel_hi:[0,1]
	v_pk_mul_f32 v[192:193], v[188:189], v[140:141] op_sel_hi:[0,1]
	v_cvt_f32_f16_e32 v194, v166
	v_cvt_f32_f16_sdwa v195, v166 dst_sel:DWORD dst_unused:UNUSED_PAD src0_sel:WORD_1
	v_cvt_f32_f16_e32 v196, v167
	v_cvt_f32_f16_sdwa v197, v167 dst_sel:DWORD dst_unused:UNUSED_PAD src0_sel:WORD_1
	v_pk_fma_f32 v[14:15], v[190:191], v[194:195], v[14:15]
	v_pk_fma_f32 v[16:17], v[192:193], v[196:197], v[16:17]
	v_mul_f32_e32 v190, 0xbfb8aa3b, v14
	v_mul_f32_e32 v191, 0xbfb8aa3b, v15
	v_mul_f32_e32 v192, 0xbfb8aa3b, v16
	v_mul_f32_e32 v193, 0xbfb8aa3b, v17
	v_exp_f32_e32 v190, v190
	v_exp_f32_e32 v191, v191
	v_exp_f32_e32 v192, v192
	v_exp_f32_e32 v193, v193
	v_add_f32_e32 v190, 1.0, v190
	v_add_f32_e32 v191, 1.0, v191
	v_add_f32_e32 v192, 1.0, v192
	v_add_f32_e32 v193, 1.0, v193
	v_rcp_f32_e32 v190, v190
	v_rcp_f32_e32 v191, v191
	v_rcp_f32_e32 v192, v192
	v_rcp_f32_e32 v193, v193
	s_nop 0
	v_pk_mul_f32 v[14:15], v[14:15], v[190:191]
	v_pk_mul_f32 v[16:17], v[16:17], v[192:193]
	v_pk_mul_f32 v[14:15], v[10:11], v[14:15]
	v_pk_mul_f32 v[16:17], v[12:13], v[16:17]
	v_cvt_pk_f16_f32 v14, v14, v15
	v_cvt_pk_f16_f32 v15, v16, v17
	global_store_dwordx2 v183, v[14:15], s[96:97]
	v_pk_mul_f32 v[6:7], v[6:7], v[146:147]
	v_pk_mul_f32 v[8:9], v[8:9], v[148:149]
	v_pk_mul_f32 v[190:191], v[186:187], v[142:143] op_sel_hi:[0,1]
	v_pk_mul_f32 v[192:193], v[186:187], v[144:145] op_sel_hi:[0,1]
	v_cvt_f32_f16_e32 v194, v164
	v_cvt_f32_f16_sdwa v195, v164 dst_sel:DWORD dst_unused:UNUSED_PAD src0_sel:WORD_1
	v_cvt_f32_f16_e32 v196, v165
	v_cvt_f32_f16_sdwa v197, v165 dst_sel:DWORD dst_unused:UNUSED_PAD src0_sel:WORD_1
	v_pk_fma_f32 v[6:7], v[190:191], v[194:195], v[6:7]
	v_pk_fma_f32 v[8:9], v[192:193], v[196:197], v[8:9]
	v_pk_mul_f32 v[190:191], v[188:189], v[150:151] op_sel_hi:[0,1]
	v_pk_mul_f32 v[192:193], v[188:189], v[152:153] op_sel_hi:[0,1]
	v_cvt_f32_f16_e32 v194, v168
	v_cvt_f32_f16_sdwa v195, v168 dst_sel:DWORD dst_unused:UNUSED_PAD src0_sel:WORD_1
	v_cvt_f32_f16_e32 v196, v169
	v_cvt_f32_f16_sdwa v197, v169 dst_sel:DWORD dst_unused:UNUSED_PAD src0_sel:WORD_1
	v_pk_fma_f32 v[6:7], v[190:191], v[194:195], v[6:7]
	v_pk_fma_f32 v[8:9], v[192:193], v[196:197], v[8:9]
	v_mul_f32_e32 v190, 0xbfb8aa3b, v6
	v_mul_f32_e32 v191, 0xbfb8aa3b, v7
	v_mul_f32_e32 v192, 0xbfb8aa3b, v8
	v_mul_f32_e32 v193, 0xbfb8aa3b, v9
	v_exp_f32_e32 v190, v190
	v_exp_f32_e32 v191, v191
	v_exp_f32_e32 v192, v192
	v_exp_f32_e32 v193, v193
	v_add_f32_e32 v190, 1.0, v190
	v_add_f32_e32 v191, 1.0, v191
	v_add_f32_e32 v192, 1.0, v192
	v_add_f32_e32 v193, 1.0, v193
	v_rcp_f32_e32 v190, v190
	v_rcp_f32_e32 v191, v191
	v_rcp_f32_e32 v192, v192
	v_rcp_f32_e32 v193, v193
	s_nop 0
	v_pk_mul_f32 v[6:7], v[6:7], v[190:191]
	v_pk_mul_f32 v[8:9], v[8:9], v[192:193]
	v_pk_mul_f32 v[6:7], v[2:3], v[6:7]
	v_pk_mul_f32 v[8:9], v[4:5], v[8:9]
	v_cvt_pk_f16_f32 v6, v6, v7
	v_cvt_pk_f16_f32 v7, v8, v9
	global_store_dwordx2 v183, v[6:7], s[96:97] offset:32
	s_mov_b64 exec, s[4:5]
	s_cmp_lg_u32 s35, 0
	s_cbranch_scc1 .Lp4_cont
	s_branch .LBB0_1135
